# strategy 8 on MLA QK: all 12 K-fragment ds_read_b128 of a tile issued up front into phase-unused VGPRs v[148:195], each MFMA behind its own counted lgkmcnt
# speedup vs baseline: 1.0144x; 1.0144x over previous
; __device__ __forceinline__ int crow(int r, int hi) { return (r & 3) + 8 * (r >> 2) + 4 * hi; }
; template <int DK, int MODE>
; __device__ __forceinline__ void attn_unit(const bf16_t* Q, int ldq, const bf16_t* K, int ldk, const bf16_t* V, int ldv, bf16_t* O, int ldo, int qb, char* shm, float sc) {
;     ...
;     auto att_compute = [&](int it, int tt, char* buf) __attribute__((always_inline)) {
;         const int kbase = tt * 64;
;         bool active = !(kbase > qb * 256 + wid * 32 + 31);
;         if (MODE == 1) active = active && (wminR < SB_SAT);
;         if (active) {
;         f32x16 p0 = f32x16{}, p1 = f32x16{};
;         const char* kp = buf + r32 * L::KS + hi * 16;
; #pragma unroll
;         for (int s = 0; s < NS; ++s) {
;             const bf16x8 a0 = *(const bf16x8*)(kp + s * 32), a1 = *(const bf16x8*)(kp + 32 * L::KS + s * 32);
;             p0 = __builtin_amdgcn_mfma_f32_32x32x16_bf16(a0, qf[s], p0, 0, 0, 0);
;             p1 = __builtin_amdgcn_mfma_f32_32x32x16_bf16(a1, qf[s], p1, 0, 0, 0);
;         }
;         const bool diag = (kbase + 63 >= qb * 256 + wid * 32);
;         bf16x8 pf[4];
;         if (MODE == 0) {
; #pragma unroll
;             for (int r = 0; r < 16; ++r) { p0[r] *= sc; p1[r] *= sc; }
;             if (diag) {
; #pragma unroll
;                 for (int r = 0; r < 16; ++r) { const int key = kbase + crow(r, hi); if (key > qpos) p0[r] = -INFINITY; if (key + 32 > qpos) p1[r] = -INFINITY; }
.LBB0_1365:
	s_or_b64 exec, exec, s[28:29]
	v_lshl_add_u64 v[32:33], s[0:1], 0, v[118:119]
	v_lshlrev_b64 v[32:33], 10, v[32:33]
	v_lshl_add_u64 v[32:33], v[122:123], 0, v[32:33]
	global_load_dwordx4 v[100:103], v[32:33], off
	s_sub_i32 s0, s31, 63
	s_cmp_gt_i32 s0, s30
	s_cbranch_scc1 .LBB0_1369
	ds_read_b128 v[148:151], v140
	ds_read_b128 v[152:155], v140 offset:6656
	ds_read_b128 v[156:159], v140 offset:32
	ds_read_b128 v[160:163], v140 offset:6688
	ds_read_b128 v[164:167], v140 offset:64
	ds_read_b128 v[168:171], v140 offset:6720
	ds_read_b128 v[172:175], v140 offset:96
	ds_read_b128 v[176:179], v140 offset:6752
	ds_read_b128 v[180:183], v140 offset:128
	ds_read_b128 v[184:187], v140 offset:6784
	ds_read_b128 v[188:191], v140 offset:160
	ds_read_b128 v[192:195], v140 offset:6816
	s_cmp_lt_i32 s31, s9
	s_waitcnt lgkmcnt(11)
	v_mfma_f32_32x32x16_bf16 v[48:63], v[148:151], v[64:67], 0
	s_waitcnt lgkmcnt(10)
	v_mfma_f32_32x32x16_bf16 v[32:47], v[152:155], v[64:67], 0
	s_waitcnt lgkmcnt(9)
	v_mfma_f32_32x32x16_bf16 v[48:63], v[156:159], v[68:71], v[48:63]
	s_waitcnt lgkmcnt(8)
	v_mfma_f32_32x32x16_bf16 v[32:47], v[160:163], v[68:71], v[32:47]
	s_waitcnt lgkmcnt(7)
	v_mfma_f32_32x32x16_bf16 v[48:63], v[164:167], v[72:75], v[48:63]
	s_waitcnt lgkmcnt(6)
	v_mfma_f32_32x32x16_bf16 v[32:47], v[168:171], v[72:75], v[32:47]
	s_waitcnt lgkmcnt(5)
	v_mfma_f32_32x32x16_bf16 v[48:63], v[172:175], v[76:79], v[48:63]
	s_waitcnt lgkmcnt(4)
	v_mfma_f32_32x32x16_bf16 v[32:47], v[176:179], v[76:79], v[32:47]
	s_waitcnt lgkmcnt(3)
	v_mfma_f32_32x32x16_bf16 v[48:63], v[180:183], v[80:83], v[48:63]
	s_waitcnt lgkmcnt(2)
	v_mfma_f32_32x32x16_bf16 v[32:47], v[184:187], v[80:83], v[32:47]
	s_waitcnt lgkmcnt(1)
	v_mfma_f32_32x32x16_bf16 v[48:63], v[188:191], v[84:87], v[48:63]
	s_waitcnt lgkmcnt(0)
	v_mfma_f32_32x32x16_bf16 v[32:47], v[192:195], v[84:87], v[32:47]
	s_nop 9
	v_mul_f32_e64 v62, v62, s24
	v_mul_f32_e64 v63, v63, s24
	v_mul_f32_e64 v60, v60, s24
	v_mul_f32_e64 v61, v61, s24
	v_mul_f32_e64 v58, v58, s24
	v_mul_f32_e64 v59, v59, s24
	v_pk_mul_f32 v[56:57], v[56:57], s[24:25] op_sel_hi:[1,0]
	v_pk_mul_f32 v[54:55], v[54:55], s[24:25] op_sel_hi:[1,0]
	v_pk_mul_f32 v[52:53], v[52:53], s[24:25] op_sel_hi:[1,0]
	v_pk_mul_f32 v[50:51], v[50:51], s[24:25] op_sel_hi:[1,0]
	v_pk_mul_f32 v[48:49], v[48:49], s[24:25] op_sel_hi:[1,0]
	v_pk_mul_f32 v[126:127], v[46:47], s[24:25] op_sel_hi:[1,0]
	v_pk_mul_f32 v[128:129], v[44:45], s[24:25] op_sel_hi:[1,0]
	v_pk_mul_f32 v[130:131], v[42:43], s[24:25] op_sel_hi:[1,0]
	v_pk_mul_f32 v[132:133], v[40:41], s[24:25] op_sel_hi:[1,0]
	v_pk_mul_f32 v[46:47], v[38:39], s[24:25] op_sel_hi:[1,0]
	v_pk_mul_f32 v[44:45], v[36:37], s[24:25] op_sel_hi:[1,0]
	v_pk_mul_f32 v[40:41], v[34:35], s[24:25] op_sel_hi:[1,0]
	v_pk_mul_f32 v[36:37], v[32:33], s[24:25] op_sel_hi:[1,0]
	s_cbranch_scc1 .LBB0_1368
	v_add_u32_e32 v32, s31, v134
	v_subrev_u32_e32 v34, 31, v32
	v_subrev_u32_e32 v33, 63, v32
	v_cmp_le_i32_e32 vcc, v34, v112
	s_nop 1
	v_cndmask_b32_e32 v36, v243, v36, vcc
	v_cmp_lt_i32_e32 vcc, v33, v112
	s_nop 1
	v_cndmask_b32_e32 v49, v243, v49, vcc
	v_cmp_le_i32_e32 vcc, v33, v112
	v_subrev_u32_e32 v33, 30, v32
	s_nop 0
	v_cndmask_b32_e32 v48, v243, v48, vcc
	v_cmp_le_i32_e32 vcc, v33, v112
	v_subrev_u32_e32 v33, 61, v32
	s_nop 0
	v_cndmask_b32_e32 v37, v243, v37, vcc
	v_cmp_le_i32_e32 vcc, v33, v112
	v_subrev_u32_e32 v33, 29, v32
	s_nop 0
	v_cndmask_b32_e32 v50, v243, v50, vcc
	v_cmp_le_i32_e32 vcc, v33, v112
	v_subrev_u32_e32 v33, 60, v32
	s_nop 0
	v_cndmask_b32_e32 v40, v243, v40, vcc
	v_cmp_le_i32_e32 vcc, v33, v112
	v_subrev_u32_e32 v33, 28, v32
	s_nop 0
	v_cndmask_b32_e32 v51, v243, v51, vcc
	v_cmp_le_i32_e32 vcc, v33, v112
	v_subrev_u32_e32 v33, 55, v32
	s_nop 0
	v_cndmask_b32_e32 v41, v243, v41, vcc
	v_cmp_le_i32_e32 vcc, v33, v112
	v_subrev_u32_e32 v33, 23, v32
	s_nop 0
	v_cndmask_b32_e32 v52, v243, v52, vcc
	v_cmp_le_i32_e32 vcc, v33, v112
	v_subrev_u32_e32 v33, 54, v32
	s_nop 0
	v_cndmask_b32_e32 v44, v243, v44, vcc
	v_cmp_le_i32_e32 vcc, v33, v112
	v_subrev_u32_e32 v33, 22, v32
	s_nop 0
	v_cndmask_b32_e32 v53, v243, v53, vcc
	v_cmp_le_i32_e32 vcc, v33, v112
	v_subrev_u32_e32 v33, 53, v32
	s_nop 0
	v_cndmask_b32_e32 v45, v243, v45, vcc
	v_cmp_le_i32_e32 vcc, v33, v112
	v_subrev_u32_e32 v33, 21, v32
	s_nop 0
	v_cndmask_b32_e32 v54, v243, v54, vcc
	v_cmp_le_i32_e32 vcc, v33, v112
	v_subrev_u32_e32 v33, 52, v32
	s_nop 0
	v_cndmask_b32_e32 v46, v243, v46, vcc
	v_cmp_le_i32_e32 vcc, v33, v112
	v_subrev_u32_e32 v33, 20, v32
	s_nop 0
	v_cndmask_b32_e32 v55, v243, v55, vcc
	v_cmp_le_i32_e32 vcc, v33, v112
	v_subrev_u32_e32 v33, 47, v32
	s_nop 0
	v_cndmask_b32_e32 v47, v243, v47, vcc
	v_cmp_le_i32_e32 vcc, v33, v112
	v_add_u32_e32 v33, -15, v32
	s_nop 0
	v_cndmask_b32_e32 v56, v243, v56, vcc
	v_cmp_le_i32_e32 vcc, v33, v112
	v_subrev_u32_e32 v33, 46, v32
	s_nop 0
	v_cndmask_b32_e32 v132, v243, v132, vcc
	v_cmp_le_i32_e32 vcc, v33, v112
	v_add_u32_e32 v33, -14, v32
	s_nop 0
	v_cndmask_b32_e32 v57, v243, v57, vcc
	v_cmp_le_i32_e32 vcc, v33, v112
	v_subrev_u32_e32 v33, 45, v32
	s_nop 0
	v_cndmask_b32_e32 v133, v243, v133, vcc
	v_cmp_le_i32_e32 vcc, v33, v112
	v_add_u32_e32 v33, -13, v32
	s_nop 0
	v_cndmask_b32_e32 v58, v243, v58, vcc
	v_cmp_le_i32_e32 vcc, v33, v112
	v_subrev_u32_e32 v33, 44, v32
	s_nop 0
	v_cndmask_b32_e32 v130, v243, v130, vcc
	v_cmp_le_i32_e32 vcc, v33, v112
	v_add_u32_e32 v33, -12, v32
	s_nop 0
	v_cndmask_b32_e32 v59, v243, v59, vcc
	v_cmp_le_i32_e32 vcc, v33, v112
	v_subrev_u32_e32 v33, 39, v32
	s_nop 0
	v_cndmask_b32_e32 v131, v243, v131, vcc
	v_cmp_le_i32_e32 vcc, v33, v112
	v_add_u32_e32 v33, -7, v32
	s_nop 0
	v_cndmask_b32_e32 v60, v243, v60, vcc
	v_cmp_le_i32_e32 vcc, v33, v112
	v_subrev_u32_e32 v33, 38, v32
	s_nop 0
	v_cndmask_b32_e32 v128, v243, v128, vcc
	v_cmp_le_i32_e32 vcc, v33, v112
	v_add_u32_e32 v33, -6, v32
	s_nop 0
	v_cndmask_b32_e32 v61, v243, v61, vcc
	v_cmp_le_i32_e32 vcc, v33, v112
	v_subrev_u32_e32 v33, 37, v32
	s_nop 0
	v_cndmask_b32_e32 v129, v243, v129, vcc
	v_cmp_le_i32_e32 vcc, v33, v112
	v_add_u32_e32 v33, -5, v32
	s_nop 0
	v_cndmask_b32_e32 v62, v243, v62, vcc
	v_cmp_le_i32_e32 vcc, v33, v112
	v_subrev_u32_e32 v33, 36, v32
	v_add_u32_e32 v32, -4, v32
	v_cndmask_b32_e32 v126, v243, v126, vcc
	v_cmp_le_i32_e32 vcc, v33, v112
	s_nop 1
	v_cndmask_b32_e32 v63, v243, v63, vcc
	v_cmp_le_i32_e32 vcc, v32, v112
	s_nop 1
	v_cndmask_b32_e32 v127, v243, v127, vcc

; __device__ __forceinline__ int crow(int r, int hi) { return (r & 3) + 8 * (r >> 2) + 4 * hi; }
; template <int DK, int MODE>
; __device__ __forceinline__ void attn_unit(const bf16_t* Q, int ldq, const bf16_t* K, int ldk, const bf16_t* V, int ldv, bf16_t* O, int ldo, int qb, char* shm, float sc) {
;     ...
;     auto att_compute = [&](int it, int tt, char* buf) __attribute__((always_inline)) {
;         const int kbase = tt * 64;
;         bool active = !(kbase > qb * 256 + wid * 32 + 31);
;         if (MODE == 1) active = active && (wminR < SB_SAT);
;         if (active) {
;         f32x16 p0 = f32x16{}, p1 = f32x16{};
;         const char* kp = buf + r32 * L::KS + hi * 16;
; #pragma unroll
;         for (int s = 0; s < NS; ++s) {
;             const bf16x8 a0 = *(const bf16x8*)(kp + s * 32), a1 = *(const bf16x8*)(kp + 32 * L::KS + s * 32);
;             p0 = __builtin_amdgcn_mfma_f32_32x32x16_bf16(a0, qf[s], p0, 0, 0, 0);
;             p1 = __builtin_amdgcn_mfma_f32_32x32x16_bf16(a1, qf[s], p1, 0, 0, 0);
;         }
;         const bool diag = (kbase + 63 >= qb * 256 + wid * 32);
;         bf16x8 pf[4];
;         if (MODE == 0) {
; #pragma unroll
;             for (int r = 0; r < 16; ++r) { p0[r] *= sc; p1[r] *= sc; }
;             if (diag) {
; #pragma unroll
;                 for (int r = 0; r < 16; ++r) { const int key = kbase + crow(r, hi); if (key > qpos) p0[r] = -INFINITY; if (key + 32 > qpos) p1[r] = -INFINITY; }
.LBB0_1373:
	s_or_b64 exec, exec, s[28:29]
	v_lshl_add_u64 v[32:33], s[0:1], 0, v[118:119]
	v_lshlrev_b64 v[32:33], 10, v[32:33]
	v_lshl_add_u64 v[32:33], v[122:123], 0, v[32:33]
	global_load_dwordx4 v[108:111], v[32:33], off
	s_add_i32 s0, s31, 1
	s_cmp_gt_i32 s0, s30
	s_cbranch_scc1 .LBB0_1360
	ds_read_b128 v[148:151], v140 offset:21504
	ds_read_b128 v[152:155], v140 offset:28160
	ds_read_b128 v[156:159], v140 offset:21536
	ds_read_b128 v[160:163], v140 offset:28192
	ds_read_b128 v[164:167], v140 offset:21568
	ds_read_b128 v[168:171], v140 offset:28224
	ds_read_b128 v[172:175], v140 offset:21600
	ds_read_b128 v[176:179], v140 offset:28256
	ds_read_b128 v[180:183], v140 offset:21632
	ds_read_b128 v[184:187], v140 offset:28288
	ds_read_b128 v[188:191], v140 offset:21664
	ds_read_b128 v[192:195], v140 offset:28320
	s_add_i32 s0, s31, 64
	s_cmp_lt_i32 s0, s9
	s_waitcnt lgkmcnt(11)
	v_mfma_f32_32x32x16_bf16 v[48:63], v[148:151], v[64:67], 0
	s_waitcnt lgkmcnt(10)
	v_mfma_f32_32x32x16_bf16 v[32:47], v[152:155], v[64:67], 0
	s_waitcnt lgkmcnt(9)
	v_mfma_f32_32x32x16_bf16 v[48:63], v[156:159], v[68:71], v[48:63]
	s_waitcnt lgkmcnt(8)
	v_mfma_f32_32x32x16_bf16 v[32:47], v[160:163], v[68:71], v[32:47]
	s_waitcnt lgkmcnt(7)
	v_mfma_f32_32x32x16_bf16 v[48:63], v[164:167], v[72:75], v[48:63]
	s_waitcnt lgkmcnt(6)
	v_mfma_f32_32x32x16_bf16 v[32:47], v[168:171], v[72:75], v[32:47]
	s_waitcnt lgkmcnt(5)
	v_mfma_f32_32x32x16_bf16 v[48:63], v[172:175], v[76:79], v[48:63]
	s_waitcnt lgkmcnt(4)
	v_mfma_f32_32x32x16_bf16 v[32:47], v[176:179], v[76:79], v[32:47]
	s_waitcnt lgkmcnt(3)
	v_mfma_f32_32x32x16_bf16 v[48:63], v[180:183], v[80:83], v[48:63]
	s_waitcnt lgkmcnt(2)
	v_mfma_f32_32x32x16_bf16 v[32:47], v[184:187], v[80:83], v[32:47]
	s_waitcnt lgkmcnt(1)
	v_mfma_f32_32x32x16_bf16 v[48:63], v[188:191], v[84:87], v[48:63]
	s_waitcnt lgkmcnt(0)
	v_mfma_f32_32x32x16_bf16 v[32:47], v[192:195], v[84:87], v[32:47]
	s_nop 9
	v_mul_f32_e64 v62, v62, s24
	v_mul_f32_e64 v63, v63, s24
	v_mul_f32_e64 v60, v60, s24
	v_mul_f32_e64 v61, v61, s24
	v_mul_f32_e64 v58, v58, s24
	v_mul_f32_e64 v59, v59, s24
	v_pk_mul_f32 v[56:57], v[56:57], s[24:25] op_sel_hi:[1,0]
	v_pk_mul_f32 v[54:55], v[54:55], s[24:25] op_sel_hi:[1,0]
	v_pk_mul_f32 v[52:53], v[52:53], s[24:25] op_sel_hi:[1,0]
	v_pk_mul_f32 v[50:51], v[50:51], s[24:25] op_sel_hi:[1,0]
	v_pk_mul_f32 v[48:49], v[48:49], s[24:25] op_sel_hi:[1,0]
	v_pk_mul_f32 v[126:127], v[46:47], s[24:25] op_sel_hi:[1,0]
	v_pk_mul_f32 v[128:129], v[44:45], s[24:25] op_sel_hi:[1,0]
	v_pk_mul_f32 v[130:131], v[42:43], s[24:25] op_sel_hi:[1,0]
	v_pk_mul_f32 v[132:133], v[40:41], s[24:25] op_sel_hi:[1,0]
	v_pk_mul_f32 v[46:47], v[38:39], s[24:25] op_sel_hi:[1,0]
	v_pk_mul_f32 v[44:45], v[36:37], s[24:25] op_sel_hi:[1,0]
	v_pk_mul_f32 v[40:41], v[34:35], s[24:25] op_sel_hi:[1,0]
	v_pk_mul_f32 v[36:37], v[32:33], s[24:25] op_sel_hi:[1,0]
	s_cbranch_scc1 .LBB0_1359
	v_add_u32_e32 v32, s31, v134
	v_add_u32_e32 v34, 33, v32
	v_add_u32_e32 v33, 1, v32
	v_cmp_le_i32_e32 vcc, v34, v112
	s_nop 1
	v_cndmask_b32_e32 v36, v243, v36, vcc
	v_cmp_lt_i32_e32 vcc, v33, v112
	s_nop 1
	v_cndmask_b32_e32 v49, v243, v49, vcc
	v_cmp_le_i32_e32 vcc, v33, v112
	v_add_u32_e32 v33, 34, v32
	s_nop 0
	v_cndmask_b32_e32 v48, v243, v48, vcc
	v_cmp_le_i32_e32 vcc, v33, v112
	v_add_u32_e32 v33, 3, v32
	s_nop 0
	v_cndmask_b32_e32 v37, v243, v37, vcc
	v_cmp_le_i32_e32 vcc, v33, v112
	v_add_u32_e32 v33, 35, v32
	s_nop 0
	v_cndmask_b32_e32 v50, v243, v50, vcc
	v_cmp_le_i32_e32 vcc, v33, v112
	v_add_u32_e32 v33, 4, v32
	s_nop 0
	v_cndmask_b32_e32 v40, v243, v40, vcc
	v_cmp_le_i32_e32 vcc, v33, v112
	v_add_u32_e32 v33, 36, v32
	s_nop 0
	v_cndmask_b32_e32 v51, v243, v51, vcc
	v_cmp_le_i32_e32 vcc, v33, v112
	v_add_u32_e32 v33, 9, v32
	s_nop 0
	v_cndmask_b32_e32 v41, v243, v41, vcc
	v_cmp_le_i32_e32 vcc, v33, v112
	v_add_u32_e32 v33, 41, v32
	s_nop 0
	v_cndmask_b32_e32 v52, v243, v52, vcc
	v_cmp_le_i32_e32 vcc, v33, v112
	v_add_u32_e32 v33, 10, v32
	s_nop 0
	v_cndmask_b32_e32 v44, v243, v44, vcc
	v_cmp_le_i32_e32 vcc, v33, v112
	v_add_u32_e32 v33, 42, v32
	s_nop 0
	v_cndmask_b32_e32 v53, v243, v53, vcc
	v_cmp_le_i32_e32 vcc, v33, v112
	v_add_u32_e32 v33, 11, v32
	s_nop 0
	v_cndmask_b32_e32 v45, v243, v45, vcc
	v_cmp_le_i32_e32 vcc, v33, v112
	v_add_u32_e32 v33, 43, v32
	s_nop 0
	v_cndmask_b32_e32 v54, v243, v54, vcc
	v_cmp_le_i32_e32 vcc, v33, v112
	v_add_u32_e32 v33, 12, v32
	s_nop 0
	v_cndmask_b32_e32 v46, v243, v46, vcc
	v_cmp_le_i32_e32 vcc, v33, v112
	v_add_u32_e32 v33, 44, v32
	s_nop 0
	v_cndmask_b32_e32 v55, v243, v55, vcc
	v_cmp_le_i32_e32 vcc, v33, v112
	v_add_u32_e32 v33, 17, v32
	s_nop 0
	v_cndmask_b32_e32 v47, v243, v47, vcc
	v_cmp_le_i32_e32 vcc, v33, v112
	v_add_u32_e32 v33, 49, v32
	s_nop 0
	v_cndmask_b32_e32 v56, v243, v56, vcc
	v_cmp_le_i32_e32 vcc, v33, v112
	v_add_u32_e32 v33, 18, v32
	s_nop 0
	v_cndmask_b32_e32 v132, v243, v132, vcc
	v_cmp_le_i32_e32 vcc, v33, v112
	v_add_u32_e32 v33, 50, v32
	s_nop 0
	v_cndmask_b32_e32 v57, v243, v57, vcc
	v_cmp_le_i32_e32 vcc, v33, v112
	v_add_u32_e32 v33, 19, v32
	s_nop 0
	v_cndmask_b32_e32 v133, v243, v133, vcc
	v_cmp_le_i32_e32 vcc, v33, v112
	v_add_u32_e32 v33, 51, v32
	s_nop 0
	v_cndmask_b32_e32 v58, v243, v58, vcc
	v_cmp_le_i32_e32 vcc, v33, v112
	v_add_u32_e32 v33, 20, v32
	s_nop 0
	v_cndmask_b32_e32 v130, v243, v130, vcc
	v_cmp_le_i32_e32 vcc, v33, v112
	v_add_u32_e32 v33, 52, v32
	s_nop 0
	v_cndmask_b32_e32 v59, v243, v59, vcc
	v_cmp_le_i32_e32 vcc, v33, v112
	v_add_u32_e32 v33, 25, v32
	s_nop 0
	v_cndmask_b32_e32 v131, v243, v131, vcc
	v_cmp_le_i32_e32 vcc, v33, v112
	v_add_u32_e32 v33, 57, v32
	s_nop 0
	v_cndmask_b32_e32 v60, v243, v60, vcc
	v_cmp_le_i32_e32 vcc, v33, v112
	v_add_u32_e32 v33, 26, v32
	s_nop 0
	v_cndmask_b32_e32 v128, v243, v128, vcc
	v_cmp_le_i32_e32 vcc, v33, v112
	v_add_u32_e32 v33, 58, v32
	s_nop 0
	v_cndmask_b32_e32 v61, v243, v61, vcc
	v_cmp_le_i32_e32 vcc, v33, v112
	v_add_u32_e32 v33, 27, v32
	s_nop 0
	v_cndmask_b32_e32 v129, v243, v129, vcc
	v_cmp_le_i32_e32 vcc, v33, v112
	v_add_u32_e32 v33, 59, v32
	s_nop 0
	v_cndmask_b32_e32 v62, v243, v62, vcc
	v_cmp_le_i32_e32 vcc, v33, v112
	v_add_u32_e32 v33, 28, v32
	v_add_u32_e32 v32, 60, v32
	v_cndmask_b32_e32 v126, v243, v126, vcc
	v_cmp_le_i32_e32 vcc, v33, v112
	s_nop 1
	v_cndmask_b32_e32 v63, v243, v63, vcc
	v_cmp_le_i32_e32 vcc, v32, v112
	s_nop 1
	v_cndmask_b32_e32 v127, v243, v127, vcc
	s_branch .LBB0_1359
